# v13 with the conversion loads fully asynchronous in the scan loader loop (no loader wait covers them; they get a whole iteration of flight time)
# speedup vs baseline: 1.0035x; 1.0035x over previous
.LBB0_206:
	v_add_u32_e32 v50, s20, v138
	v_cmp_lt_i32_e32 vcc, 0, v50
	v_lshl_add_u64 v[48:49], v[152:153], 0, s[20:21]
	v_lshl_add_u64 v[52:53], s[14:15], 0, v[154:155]
	v_cndmask_b32_e64 v50, 0, 1, vcc
	v_sub_co_u32_e32 v48, vcc, v48, v50
	v_lshl_add_u64 v[162:163], s[14:15], 0, v[150:151]
	s_nop 0
	v_subbrev_co_u32_e32 v51, vcc, 0, v49, vcc
	v_mad_u64_u32 v[48:49], s[22:23], v48, s75, v[146:147]
	v_mov_b32_e32 v50, v49
	v_mad_u64_u32 v[50:51], s[22:23], v51, s75, v[50:51]
	s_mov_b32 s22, 0x287d8000
	s_nop 0
	v_add_co_u32_e32 v54, vcc, s22, v52
	s_mov_b32 s22, 0x287d9000
	s_nop 0
	v_addc_co_u32_e32 v55, vcc, 0, v53, vcc
	v_add_co_u32_e32 v52, vcc, s22, v52
	v_mov_b32_e32 v49, v50
	s_nop 0
	v_addc_co_u32_e32 v53, vcc, 0, v53, vcc
	global_load_dwordx4 v[80:83], v[54:55], off offset:2048
	global_load_dwordx4 v[76:79], v[52:53], off
	v_add_co_u32_e32 v54, vcc, s74, v48
	s_nop 1
	v_addc_co_u32_e32 v55, vcc, 0, v50, vcc
	v_add_co_u32_e32 v50, vcc, 0x31730000, v162
	global_load_dwordx4 v[112:115], v[52:53], off offset:2048
	global_load_dwordx4 v[72:75], v[54:55], off
	v_addc_co_u32_e32 v51, vcc, 0, v163, vcc
	global_load_dwordx4 v[116:119], v[54:55], off offset:2048
	s_nop 0
	global_load_dwordx4 v[52:55], v[50:51], off
	v_add_co_u32_e32 v50, vcc, 0x33730000, v162
	v_addc_co_u32_e32 v51, vcc, 0, v163, vcc
	global_load_dwordx4 v[84:87], v[48:49], off offset:2048
	s_nop 0
	global_load_dwordx4 v[48:51], v[50:51], off
	s_and_b64 vcc, exec, s[44:45]
	s_cbranch_vccnz .LBB0_208
	v_add_co_u32_e32 v96, vcc, 0x37730000, v162
	s_nop 1
	v_addc_co_u32_e32 v97, vcc, 0, v163, vcc
	v_add_co_u32_e32 v108, vcc, 0x26730000, v162
	s_nop 1
	v_addc_co_u32_e32 v109, vcc, 0, v163, vcc
	global_load_dwordx4 v[96:99], v[96:97], off
	s_nop 0
	global_load_dwordx4 v[108:111], v[108:109], off
.LBB0_208:
	s_cmp_eq_u32 s53, 1
	s_cbranch_scc0 .Lcis_b_done
	s_waitcnt vmcnt(9)
	s_cmp_eq_u32 s56, 1
	s_cbranch_scc0 .Lcis_b_nogs
	v_pk_mul_f32 v[232:233], v[232:233], v[208:209]
	v_pk_mul_f32 v[234:235], v[234:235], v[210:211]
	v_pk_mul_f32 v[236:237], v[236:237], v[212:213]
	v_pk_mul_f32 v[238:239], v[238:239], v[214:215]
	v_pk_mul_f32 v[240:241], v[240:241], v[216:217]
	v_pk_mul_f32 v[242:243], v[242:243], v[218:219]
	v_pk_mul_f32 v[244:245], v[244:245], v[220:221]
	v_pk_mul_f32 v[246:247], v[246:247], v[222:223]

.LBB0_212:
	s_or_b64 exec, exec, s[22:23]
	s_and_b32 s22, s24, 0x800
	s_addk_i32 s24, 0x800
	v_add_u32_e32 v40, s22, v171
	s_add_u32 s20, s20, 32
	ds_read_b64 v[40:41], v40
	s_addc_u32 s21, s21, 0
	s_mov_b64 s[22:23], 0x48000
	s_add_i32 s19, s19, 1
	s_waitcnt lgkmcnt(0)
	v_cvt_pk_bf16_f32 v42, v40, v41
	v_lshl_add_u64 v[40:41], s[14:15], 0, v[148:149]
	v_lshl_add_u64 v[148:149], v[148:149], 0, s[92:93]
	v_lshl_add_u64 v[150:151], v[150:151], 0, s[92:93]
	v_lshl_add_u64 v[154:155], v[154:155], 0, s[22:23]
	s_cmpk_eq_i32 s20, 0xfa0
	global_store_dword v[40:41], v42, off
	s_barrier
	s_cbranch_scc1 .LBB0_214
	s_cmp_eq_u32 s53, 1
	s_cbranch_scc0 .Lcis_w1
	s_cmp_eq_u32 s56, 1
	s_cbranch_scc1 .Lcis_w21
	s_cmp_eq_u32 s56, 2
	s_cbranch_scc1 .Lcis_w5
	s_waitcnt vmcnt(17)
	s_branch .Lcis_wd
.Lcis_w21:
	s_waitcnt vmcnt(21)
	s_branch .Lcis_wd
.Lcis_w5:
	s_waitcnt vmcnt(5)
	s_branch .Lcis_wd
.Lcis_w1:
	s_waitcnt vmcnt(1)
.Lcis_wd:
	v_mov_b64_e32 v[92:93], v[108:109]
	v_mov_b64_e32 v[88:89], v[96:97]
	v_mov_b64_e32 v[40:41], v[48:49]
	v_mov_b64_e32 v[44:45], v[52:53]
	v_mov_b64_e32 v[104:105], v[116:117]
	v_mov_b64_e32 v[100:101], v[112:113]
	v_mov_b64_e32 v[56:57], v[72:73]
	v_mov_b64_e32 v[64:65], v[76:77]
	v_mov_b64_e32 v[60:61], v[84:85]
	v_mov_b64_e32 v[68:69], v[80:81]
	v_mov_b64_e32 v[94:95], v[110:111]
	v_mov_b64_e32 v[90:91], v[98:99]
	v_mov_b64_e32 v[42:43], v[50:51]
	v_mov_b64_e32 v[46:47], v[54:55]
	v_mov_b64_e32 v[106:107], v[118:119]
	v_mov_b64_e32 v[102:103], v[114:115]
	v_mov_b64_e32 v[58:59], v[74:75]
	v_mov_b64_e32 v[66:67], v[78:79]
	v_mov_b64_e32 v[62:63], v[86:87]
	v_mov_b64_e32 v[70:71], v[82:83]
	s_branch .LBB0_206
.LBB0_214:
	s_waitcnt vmcnt(0)
	v_lshlrev_b32_e32 v56, 16, v116
	v_and_b32_e32 v57, 0xffff0000, v116
	v_lshlrev_b32_e32 v58, 16, v117
	v_and_b32_e32 v59, 0xffff0000, v117
	v_lshlrev_b32_e32 v60, 16, v118
	v_and_b32_e32 v61, 0xffff0000, v118
	v_lshlrev_b32_e32 v62, 16, v119
	v_and_b32_e32 v63, 0xffff0000, v119
	v_lshlrev_b32_e32 v40, 16, v112
	v_and_b32_e32 v41, 0xffff0000, v112
	v_lshlrev_b32_e32 v42, 16, v113
	v_and_b32_e32 v43, 0xffff0000, v113
	v_lshlrev_b32_e32 v44, 16, v114
	v_and_b32_e32 v45, 0xffff0000, v114
	v_lshlrev_b32_e32 v46, 16, v115
	v_and_b32_e32 v47, 0xffff0000, v115
	v_cndmask_b32_e64 v62, v62, 0, s[42:43]
	v_cndmask_b32_e64 v63, v63, 0, s[42:43]
	v_cndmask_b32_e64 v60, v60, 0, s[42:43]
	v_cndmask_b32_e64 v61, v61, 0, s[42:43]
	v_cndmask_b32_e64 v58, v58, 0, s[42:43]
	v_cndmask_b32_e64 v59, v59, 0, s[42:43]
	v_cndmask_b32_e64 v56, v56, 0, s[42:43]
	v_cndmask_b32_e64 v57, v57, 0, s[42:43]
	v_sub_f32_e32 v57, v57, v41
	v_sub_f32_e32 v56, v56, v40
	v_sub_f32_e32 v59, v59, v43
	v_sub_f32_e32 v58, v58, v42
	v_sub_f32_e32 v61, v61, v45
	v_sub_f32_e32 v60, v60, v44
	v_sub_f32_e32 v63, v63, v47
	v_sub_f32_e32 v62, v62, v46
	v_pk_fma_f32 v[38:39], v[38:39], v[62:63], v[46:47]
	v_pk_fma_f32 v[36:37], v[36:37], v[60:61], v[44:45]
	v_pk_fma_f32 v[34:35], v[34:35], v[58:59], v[42:43]
	s_and_b64 vcc, exec, s[44:45]
	v_pk_fma_f32 v[32:33], v[32:33], v[56:57], v[40:41]
	s_cbranch_vccnz .LBB0_216
	s_waitcnt vmcnt(1)
	v_lshlrev_b32_e32 v40, 16, v108
	v_and_b32_e32 v41, 0xffff0000, v108
	v_lshlrev_b32_e32 v42, 16, v109
	v_and_b32_e32 v43, 0xffff0000, v109
	v_lshlrev_b32_e32 v44, 16, v110
	v_and_b32_e32 v45, 0xffff0000, v110
	v_lshlrev_b32_e32 v46, 16, v111
	v_and_b32_e32 v47, 0xffff0000, v111
	v_sub_f32_e32 v41, v41, v33
	v_sub_f32_e32 v40, v40, v32
	v_sub_f32_e32 v43, v43, v35
	v_sub_f32_e32 v42, v42, v34
	v_sub_f32_e32 v45, v45, v37
	v_sub_f32_e32 v44, v44, v36
	v_sub_f32_e32 v47, v47, v39
	v_sub_f32_e32 v46, v46, v38
	v_lshlrev_b32_e32 v56, 16, v96
	v_and_b32_e32 v57, 0xffff0000, v96
	v_lshlrev_b32_e32 v58, 16, v97
	v_and_b32_e32 v59, 0xffff0000, v97
	v_lshlrev_b32_e32 v60, 16, v98
	v_and_b32_e32 v61, 0xffff0000, v98
	v_lshlrev_b32_e32 v62, 16, v99
	v_and_b32_e32 v63, 0xffff0000, v99
	v_pk_fma_f32 v[38:39], v[46:47], v[62:63], v[38:39]
	v_pk_fma_f32 v[36:37], v[44:45], v[60:61], v[36:37]
	v_pk_fma_f32 v[34:35], v[42:43], v[58:59], v[34:35]
	v_pk_fma_f32 v[32:33], v[40:41], v[56:57], v[32:33]
